# combo6 = combo5 + prologue pos-bias moved to the last four workgroups (2 modulation items instead of 3) and 4x deeper load batching
# speedup vs baseline: 1.0043x; 1.0022x over previous
.LBB0_70:
	v_add_u32_e32 v4, s81, v40
	s_sub_i32 s100, s82, s68
	s_add_i32 s100, s100, 4
	s_mov_b32 s101, 0
	s_cmp_gt_i32 s100, -1
	v_lshlrev_b32_e32 v5, 2, v4
	s_waitcnt lgkmcnt(0)
	s_barrier
	s_cbranch_scc0 .LBB0_76
	s_add_i32 s0, 0, 0x27d60
	v_mov_b32_e32 v0, s0
	ds_read_b128 v[0:3], v0
	s_ashr_i32 s83, s82, 31
	s_lshl_b64 s[0:1], s[100:101], 20
	s_lshl_b64 s[10:11], s[100:101], 13
	v_and_b32_e32 v6, 0x7f, v4
	s_waitcnt lgkmcnt(0)
	v_readfirstlane_b32 s12, v0
	v_readfirstlane_b32 s4, v2
	v_readfirstlane_b32 s9, v1
	v_and_b32_e32 v2, 0xfffffe00, v5
	s_add_u32 s10, s12, s10
	v_readfirstlane_b32 s5, v3
	v_ashrrev_i32_e32 v3, 31, v2
	s_addc_u32 s11, s9, s11
	v_lshl_add_u64 v[0:1], v[2:3], 2, s[10:11]
	v_lshlrev_b64 v[2:3], 9, v[2:3]
	v_lshl_add_u64 v[2:3], s[0:1], 0, v[2:3]
	v_lshl_or_b32 v2, v6, 2, v2
	v_lshl_add_u64 v[2:3], s[4:5], 0, v[2:3]
	v_mov_b32_e32 v7, 0
	s_mov_b64 s[0:1], 0
	s_mov_b64 s[4:5], 0x1000
.LBB0_72:
	v_lshl_add_u64 v[16:17], v[0:1], 0, s[0:1]
	v_lshl_add_u64 v[128:129], v[2:3], 0, s[4:5]
	v_lshl_add_u64 v[130:131], v[128:129], 0, s[4:5]
	v_lshl_add_u64 v[132:133], v[130:131], 0, s[4:5]
	global_load_dwordx4 v[64:67], v[16:17], off offset:0
	global_load_dwordx4 v[68:71], v[16:17], off offset:16
	global_load_dword v96, v[2:3], off
	global_load_dword v97, v[2:3], off offset:512
	global_load_dword v98, v[2:3], off offset:1024
	global_load_dword v99, v[2:3], off offset:1536
	global_load_dword v100, v[2:3], off offset:2048
	global_load_dword v101, v[2:3], off offset:2560
	global_load_dword v102, v[2:3], off offset:3072
	global_load_dword v103, v[2:3], off offset:3584
	global_load_dwordx4 v[72:75], v[16:17], off offset:32
	global_load_dwordx4 v[76:79], v[16:17], off offset:48
	global_load_dword v104, v[128:129], off
	global_load_dword v105, v[128:129], off offset:512
	global_load_dword v106, v[128:129], off offset:1024
	global_load_dword v107, v[128:129], off offset:1536
	global_load_dword v108, v[128:129], off offset:2048
	global_load_dword v109, v[128:129], off offset:2560
	global_load_dword v110, v[128:129], off offset:3072
	global_load_dword v111, v[128:129], off offset:3584
	global_load_dwordx4 v[80:83], v[16:17], off offset:64
	global_load_dwordx4 v[84:87], v[16:17], off offset:80
	global_load_dword v112, v[130:131], off
	global_load_dword v113, v[130:131], off offset:512
	global_load_dword v114, v[130:131], off offset:1024
	global_load_dword v115, v[130:131], off offset:1536
	global_load_dword v116, v[130:131], off offset:2048
	global_load_dword v117, v[130:131], off offset:2560
	global_load_dword v118, v[130:131], off offset:3072
	global_load_dword v119, v[130:131], off offset:3584
	global_load_dwordx4 v[88:91], v[16:17], off offset:96
	global_load_dwordx4 v[92:95], v[16:17], off offset:112
	global_load_dword v120, v[132:133], off
	global_load_dword v121, v[132:133], off offset:512
	global_load_dword v122, v[132:133], off offset:1024
	global_load_dword v123, v[132:133], off offset:1536
	global_load_dword v124, v[132:133], off offset:2048
	global_load_dword v125, v[132:133], off offset:2560
	global_load_dword v126, v[132:133], off offset:3072
	global_load_dword v127, v[132:133], off offset:3584
	s_add_u32 s0, s0, 0x80
	s_addc_u32 s1, s1, 0
	v_lshl_add_u64 v[2:3], v[132:133], 0, s[4:5]
	s_cmpk_eq_i32 s0, 0x800
	s_waitcnt vmcnt(0) lgkmcnt(0)
	v_fmac_f32_e32 v7, v64, v96
	v_fmac_f32_e32 v7, v65, v97
	v_fmac_f32_e32 v7, v66, v98
	v_fmac_f32_e32 v7, v67, v99
	v_fmac_f32_e32 v7, v68, v100
	v_fmac_f32_e32 v7, v69, v101
	v_fmac_f32_e32 v7, v70, v102
	v_fmac_f32_e32 v7, v71, v103
	v_fmac_f32_e32 v7, v72, v104
	v_fmac_f32_e32 v7, v73, v105
	v_fmac_f32_e32 v7, v74, v106
	v_fmac_f32_e32 v7, v75, v107
	v_fmac_f32_e32 v7, v76, v108
	v_fmac_f32_e32 v7, v77, v109
	v_fmac_f32_e32 v7, v78, v110
	v_fmac_f32_e32 v7, v79, v111
	v_fmac_f32_e32 v7, v80, v112
	v_fmac_f32_e32 v7, v81, v113
	v_fmac_f32_e32 v7, v82, v114
	v_fmac_f32_e32 v7, v83, v115
	v_fmac_f32_e32 v7, v84, v116
	v_fmac_f32_e32 v7, v85, v117
	v_fmac_f32_e32 v7, v86, v118
	v_fmac_f32_e32 v7, v87, v119
	v_fmac_f32_e32 v7, v88, v120
	v_fmac_f32_e32 v7, v89, v121
	v_fmac_f32_e32 v7, v90, v122
	v_fmac_f32_e32 v7, v91, v123
	v_fmac_f32_e32 v7, v92, v124
	v_fmac_f32_e32 v7, v93, v125
	v_fmac_f32_e32 v7, v94, v126
	v_fmac_f32_e32 v7, v95, v127
	s_cbranch_scc0 .LBB0_72
	s_movk_i32 s0, 0x80
	v_lshl_add_u32 v0, v4, 2, 0
	v_cmp_gt_i32_e32 vcc, s0, v4
	ds_write_b32 v0, v7
	s_waitcnt lgkmcnt(0)
	s_barrier
	s_and_saveexec_b64 s[0:1], vcc
	s_cbranch_execz .LBB0_75
	v_lshl_add_u32 v2, v6, 2, 0
	ds_read2st64_b32 v[0:1], v2 offset1:2
	ds_read2st64_b32 v[2:3], v2 offset0:4 offset1:6
	v_lshl_or_b32 v6, s100, 7, v6
	v_ashrrev_i32_e32 v7, 31, v6
	v_lshl_add_u64 v[6:7], v[6:7], 2, s[6:7]
	s_waitcnt lgkmcnt(1)
	v_add_f32_e32 v0, v0, v1
	s_waitcnt lgkmcnt(0)
	v_add_f32_e32 v0, v0, v2
	v_add_f32_e32 v2, v0, v3
	v_add_co_u32_e32 v0, vcc, 0x49b00000, v6
	s_nop 1
	v_addc_co_u32_e32 v1, vcc, 0, v7, vcc
	flat_store_dword v[0:1], v2
